# v32 plus late trailing-half barrier and no redundant lgkmcnt after the load-segment barrier
# speedup vs baseline: 1.0106x; 1.0106x over previous
; #define PG8_STAGE(bufoff, gbase, voff) do { _Pragma("unroll") for (int _i = 0; _i < 2; ++_i) \
;         __builtin_amdgcn_global_load_lds((const unsigned*)((const char*)(gbase) + (voff)[_i]), (PG8_LAS unsigned*)(lds + (bufoff) + ldsw + _i * 8192), 16, 0, 0); } while (0)
; #define PG8_LDA(dst, b, h) do { _Pragma("unroll") for (int m = 0; m < 4; ++m) _Pragma("unroll") for (int k = 0; k < 2; ++k) dst[m][k] = *(const PG8_LAS bf16x8*)(lds + PG8_SA(b, h) + aoff + m * 2048 + k * 1024); } while (0)
; #define PG8_LDB(dst, b, h) do { _Pragma("unroll") for (int n = 0; n < 2; ++n) _Pragma("unroll") for (int k = 0; k < 2; ++k) dst[n][k] = *(const PG8_LAS bf16x8*)(lds + PG8_SB(b, h) + boff + n * 2048 + k * 1024); } while (0)
; #define PG8_MMA(ai, bj, At, Bt) do { __builtin_amdgcn_s_setprio(1); _Pragma("unroll") for (int m = 0; m < 4; ++m) _Pragma("unroll") for (int n = 0; n < 2; ++n) _Pragma("unroll") for (int k = 0; k < 2; ++k) \
;         acc[ai][bj][m][n] = __builtin_amdgcn_mfma_f32_16x16x32_bf16(Bt[n][k], At[m][k], acc[ai][bj][m][n], 0, 0, 0); __builtin_amdgcn_s_setprio(0); } while (0)
; #define PG8_WAIT_V(n) asm volatile("s_waitcnt vmcnt(" #n ")" ::: "memory")
; #define PG8_WAIT_L(n) asm volatile("s_waitcnt lgkmcnt(" #n ")" ::: "memory")
; #define PG8_BAR __builtin_amdgcn_s_barrier()
; #define PG8_SCHED __builtin_amdgcn_sched_barrier(0)
; template <class Epi, class Sched, bool ALIGN_EPI = false, bool SP2 = false>
; __device__ __forceinline__ void gemm_phase(PG8_LAS unsigned char* lds, const Gemm g, const Sched& S, const Epi& E, const int wid_) {
;     ...
;             PG8_LDB(B0, 0, 0); PG8_LDB(B1, 0, 1); PG8_SCHED; PG8_LDA(At, 0, 0); PG8_STAGE(PG8_SA(1, 1), a1 + hstepA, voffA);
;             PG8_WAIT_V(8); PG8_WAIT_L(0); PG8_BAR; PG8_MMA(0, 0, At, B0); PG8_MMA(0, 1, At, B1); PG8_BAR; PG8_SCHED;
;             PG8_LDA(At, 0, 1); PG8_STAGE(PG8_SB(0, 0), b2, voffB); PG8_STAGE(PG8_SB(0, 1), b2 + hstepB, voffB); PG8_STAGE(PG8_SA(0, 0), a2, voffA);
;             PG8_WAIT_V(8); PG8_WAIT_L(0); PG8_BAR; PG8_MMA(1, 0, At, B0); PG8_MMA(1, 1, At, B1); PG8_BAR; PG8_SCHED;
.Llate_bar_skip:
.LBB0_380:
	s_add_i32 s97, s38, 2
	s_add_u32 s98, s6, 0x80
	s_addc_u32 s39, s7, 0
	s_cmp_eq_u32 s41, s38
	s_cselect_b32 s39, s47, s39
	s_cselect_b32 s38, s46, s98
	s_cselect_b32 s99, s61, s62
	s_cselect_b32 s98, s60, s49
	s_add_i32 vcc_lo, 0, 0x14000
	v_add_u32_e32 v164, s42, v180
	v_add_u32_e32 v176, vcc_lo, v180
	ds_read_b128 v[128:131], v164
	ds_read_b128 v[132:135], v164 offset:1024
	ds_read_b128 v[136:139], v164 offset:2048
	ds_read_b128 v[164:167], v164 offset:3072
	ds_read_b128 v[168:171], v176
	ds_read_b128 v[172:175], v176 offset:1024
	ds_read_b128 v[182:185], v176 offset:2048
	ds_read_b128 v[186:189], v176 offset:3072
	v_lshl_add_u64 v[178:179], s[6:7], 0, v[162:163]
	s_add_i32 m0, s36, 0xc000
	ds_read_b128 v[190:193], v181
	ds_read_b128 v[194:197], v181 offset:1024
	ds_read_b128 v[198:201], v181 offset:2048
	ds_read_b128 v[202:205], v181 offset:3072
	ds_read_b128 v[206:209], v181 offset:4096
	ds_read_b128 v[212:215], v181 offset:5120
	ds_read_b128 v[216:219], v181 offset:6144
	ds_read_b128 v[220:223], v181 offset:7168
	global_load_lds_dwordx4 v[178:179], off
	v_lshl_add_u64 v[178:179], s[6:7], 0, v[160:161]
	s_add_i32 m0, s36, 0xe000
	s_nop 0
	global_load_lds_dwordx4 v[178:179], off
	s_waitcnt vmcnt(8)
	s_waitcnt lgkmcnt(0)
	s_barrier
	v_mfma_f32_16x16x32_bf16 v[124:127], v[128:131], v[190:193], v[124:127]
	v_mfma_f32_16x16x32_bf16 v[120:123], v[136:139], v[190:193], v[120:123]
	v_mfma_f32_16x16x32_bf16 v[116:119], v[128:131], v[198:201], v[116:119]
	v_mfma_f32_16x16x32_bf16 v[112:115], v[136:139], v[198:201], v[112:115]
	v_mfma_f32_16x16x32_bf16 v[100:103], v[128:131], v[206:209], v[100:103]
	v_mfma_f32_16x16x32_bf16 v[96:99], v[136:139], v[206:209], v[96:99]
	v_mfma_f32_16x16x32_bf16 v[84:87], v[128:131], v[216:219], v[84:87]
	v_mfma_f32_16x16x32_bf16 v[80:83], v[136:139], v[216:219], v[80:83]
	v_mfma_f32_16x16x32_bf16 v[124:127], v[132:135], v[194:197], v[124:127]
	v_mfma_f32_16x16x32_bf16 v[120:123], v[164:167], v[194:197], v[120:123]
	v_mfma_f32_16x16x32_bf16 v[116:119], v[132:135], v[202:205], v[116:119]
	v_mfma_f32_16x16x32_bf16 v[112:115], v[164:167], v[202:205], v[112:115]
	v_mfma_f32_16x16x32_bf16 v[100:103], v[132:135], v[212:215], v[100:103]
	v_mfma_f32_16x16x32_bf16 v[96:99], v[164:167], v[212:215], v[96:99]
	v_mfma_f32_16x16x32_bf16 v[84:87], v[132:135], v[220:223], v[84:87]
	v_mfma_f32_16x16x32_bf16 v[80:83], v[164:167], v[220:223], v[80:83]
	v_mfma_f32_16x16x32_bf16 v[108:111], v[168:171], v[190:193], v[108:111]
	v_mfma_f32_16x16x32_bf16 v[104:107], v[182:185], v[190:193], v[104:107]
	v_mfma_f32_16x16x32_bf16 v[92:95], v[168:171], v[198:201], v[92:95]
	v_mfma_f32_16x16x32_bf16 v[88:91], v[182:185], v[198:201], v[88:91]
	v_mfma_f32_16x16x32_bf16 v[76:79], v[168:171], v[206:209], v[76:79]
	v_mfma_f32_16x16x32_bf16 v[72:75], v[182:185], v[206:209], v[72:75]
	v_mfma_f32_16x16x32_bf16 v[68:71], v[168:171], v[216:219], v[68:71]
	v_mfma_f32_16x16x32_bf16 v[64:67], v[182:185], v[216:219], v[64:67]
	v_mfma_f32_16x16x32_bf16 v[108:111], v[172:175], v[194:197], v[108:111]
	v_mfma_f32_16x16x32_bf16 v[104:107], v[186:189], v[194:197], v[104:107]
	v_mfma_f32_16x16x32_bf16 v[92:95], v[172:175], v[202:205], v[92:95]
	v_mfma_f32_16x16x32_bf16 v[88:91], v[186:189], v[202:205], v[88:91]
	v_mfma_f32_16x16x32_bf16 v[76:79], v[172:175], v[212:215], v[76:79]
	v_mfma_f32_16x16x32_bf16 v[72:75], v[186:189], v[212:215], v[72:75]
	v_mfma_f32_16x16x32_bf16 v[68:71], v[172:175], v[220:223], v[68:71]
	v_mfma_f32_16x16x32_bf16 v[64:67], v[186:189], v[220:223], v[64:67]
	s_barrier
	s_add_i32 vcc_hi, s42, s83
	v_lshl_add_u64 v[178:179], s[98:99], 0, v[142:143]
	s_mov_b32 m0, vcc_hi
	ds_read_b128 v[190:193], v181 offset:16384
	ds_read_b128 v[194:197], v181 offset:17408
	ds_read_b128 v[198:201], v181 offset:18432
	ds_read_b128 v[202:205], v181 offset:19456
	ds_read_b128 v[206:209], v181 offset:20480
	ds_read_b128 v[212:215], v181 offset:21504
	ds_read_b128 v[216:219], v181 offset:22528
	ds_read_b128 v[220:223], v181 offset:23552
	global_load_lds_dwordx4 v[178:179], off
	s_add_i32 m0, vcc_hi, 0x2000
	v_lshl_add_u64 v[224:225], s[98:99], 0, v[146:147]
	s_add_u32 s98, s98, s18
	s_addc_u32 s99, s99, 0
	s_add_i32 vcc_lo, vcc_lo, s83
	global_load_lds_dwordx4 v[224:225], off
	v_lshl_add_u64 v[226:227], s[98:99], 0, v[142:143]
	s_mov_b32 m0, vcc_lo
	v_lshl_add_u64 v[228:229], s[98:99], 0, v[146:147]
	global_load_lds_dwordx4 v[226:227], off
	s_add_i32 m0, vcc_lo, 0x2000
	v_lshl_add_u64 v[230:231], s[38:39], 0, v[140:141]
	global_load_lds_dwordx4 v[228:229], off
	s_mov_b32 m0, s36
	v_lshl_add_u64 v[232:233], s[38:39], 0, v[144:145]
	global_load_lds_dwordx4 v[230:231], off
	s_mov_b32 m0, s10
	s_nop 0
	global_load_lds_dwordx4 v[232:233], off
	s_waitcnt vmcnt(8)
	s_waitcnt lgkmcnt(0)
	s_barrier
; #define PG8_STAGE(bufoff, gbase, voff) do { _Pragma("unroll") for (int _i = 0; _i < 2; ++_i) \
;         __builtin_amdgcn_global_load_lds((const unsigned*)((const char*)(gbase) + (voff)[_i]), (PG8_LAS unsigned*)(lds + (bufoff) + ldsw + _i * 8192), 16, 0, 0); } while (0)
; #define PG8_LDA(dst, b, h) do { _Pragma("unroll") for (int m = 0; m < 4; ++m) _Pragma("unroll") for (int k = 0; k < 2; ++k) dst[m][k] = *(const PG8_LAS bf16x8*)(lds + PG8_SA(b, h) + aoff + m * 2048 + k * 1024); } while (0)
; #define PG8_LDB(dst, b, h) do { _Pragma("unroll") for (int n = 0; n < 2; ++n) _Pragma("unroll") for (int k = 0; k < 2; ++k) dst[n][k] = *(const PG8_LAS bf16x8*)(lds + PG8_SB(b, h) + boff + n * 2048 + k * 1024); } while (0)
; #define PG8_MMA(ai, bj, At, Bt) do { __builtin_amdgcn_s_setprio(1); _Pragma("unroll") for (int m = 0; m < 4; ++m) _Pragma("unroll") for (int n = 0; n < 2; ++n) _Pragma("unroll") for (int k = 0; k < 2; ++k) \
;         acc[ai][bj][m][n] = __builtin_amdgcn_mfma_f32_16x16x32_bf16(Bt[n][k], At[m][k], acc[ai][bj][m][n], 0, 0, 0); __builtin_amdgcn_s_setprio(0); } while (0)
; #define PG8_WAIT_V(n) asm volatile("s_waitcnt vmcnt(" #n ")" ::: "memory")
; #define PG8_WAIT_L(n) asm volatile("s_waitcnt lgkmcnt(" #n ")" ::: "memory")
; #define PG8_BAR __builtin_amdgcn_s_barrier()
; #define PG8_SCHED __builtin_amdgcn_sched_barrier(0)
; template <class Epi, class Sched, bool ALIGN_EPI = false, bool SP2 = false>
; __device__ __forceinline__ void gemm_phase(PG8_LAS unsigned char* lds, const Gemm g, const Sched& S, const Epi& E, const int wid_) {
;     ...
;             PG8_WAIT_V(8); PG8_WAIT_L(0); PG8_BAR; PG8_MMA(1, 0, At, B0); PG8_MMA(1, 1, At, B1); PG8_BAR; PG8_SCHED;
;             PG8_LDB(B0, 1, 0); PG8_LDB(B1, 1, 1); PG8_SCHED; PG8_LDA(At, 1, 0); PG8_STAGE(PG8_SA(0, 1), a2 + hstepA, voffA);
;             PG8_WAIT_V(8); PG8_WAIT_L(0); PG8_BAR; PG8_MMA(0, 0, At, B0); PG8_MMA(0, 1, At, B1); PG8_BAR; PG8_SCHED;
;             PG8_LDA(At, 1, 1); PG8_STAGE(PG8_SB(1, 0), b3, voffB); PG8_STAGE(PG8_SB(1, 1), b3 + hstepB, voffB); PG8_STAGE(PG8_SA(1, 0), a3, voffA);
	v_mfma_f32_16x16x32_bf16 v[60:63], v[128:131], v[190:193], v[60:63]
	v_mfma_f32_16x16x32_bf16 v[56:59], v[136:139], v[190:193], v[56:59]
	v_mfma_f32_16x16x32_bf16 v[52:55], v[128:131], v[198:201], v[52:55]
	v_mfma_f32_16x16x32_bf16 v[48:51], v[136:139], v[198:201], v[48:51]
	v_mfma_f32_16x16x32_bf16 v[36:39], v[128:131], v[206:209], v[36:39]
	v_mfma_f32_16x16x32_bf16 v[32:35], v[136:139], v[206:209], v[32:35]
	v_mfma_f32_16x16x32_bf16 v[20:23], v[128:131], v[216:219], v[20:23]
	v_mfma_f32_16x16x32_bf16 v[16:19], v[136:139], v[216:219], v[16:19]
	v_mfma_f32_16x16x32_bf16 v[60:63], v[132:135], v[194:197], v[60:63]
	v_mfma_f32_16x16x32_bf16 v[56:59], v[164:167], v[194:197], v[56:59]
	v_mfma_f32_16x16x32_bf16 v[52:55], v[132:135], v[202:205], v[52:55]
	v_mfma_f32_16x16x32_bf16 v[48:51], v[164:167], v[202:205], v[48:51]
	v_mfma_f32_16x16x32_bf16 v[36:39], v[132:135], v[212:215], v[36:39]
	v_mfma_f32_16x16x32_bf16 v[32:35], v[164:167], v[212:215], v[32:35]
	v_mfma_f32_16x16x32_bf16 v[20:23], v[132:135], v[220:223], v[20:23]
	v_mfma_f32_16x16x32_bf16 v[16:19], v[164:167], v[220:223], v[16:19]
	v_mfma_f32_16x16x32_bf16 v[44:47], v[168:171], v[190:193], v[44:47]
	v_mfma_f32_16x16x32_bf16 v[40:43], v[182:185], v[190:193], v[40:43]
	v_mfma_f32_16x16x32_bf16 v[28:31], v[168:171], v[198:201], v[28:31]
	v_mfma_f32_16x16x32_bf16 v[24:27], v[182:185], v[198:201], v[24:27]
	v_mfma_f32_16x16x32_bf16 v[12:15], v[168:171], v[206:209], v[12:15]
	v_mfma_f32_16x16x32_bf16 v[8:11], v[182:185], v[206:209], v[8:11]
	v_mfma_f32_16x16x32_bf16 v[4:7], v[168:171], v[216:219], v[4:7]
	v_mfma_f32_16x16x32_bf16 v[0:3], v[182:185], v[216:219], v[0:3]
	v_mfma_f32_16x16x32_bf16 v[44:47], v[172:175], v[194:197], v[44:47]
	v_mfma_f32_16x16x32_bf16 v[40:43], v[186:189], v[194:197], v[40:43]
	v_mfma_f32_16x16x32_bf16 v[28:31], v[172:175], v[202:205], v[28:31]
	v_mfma_f32_16x16x32_bf16 v[24:27], v[186:189], v[202:205], v[24:27]
	v_mfma_f32_16x16x32_bf16 v[12:15], v[172:175], v[212:215], v[12:15]
	v_mfma_f32_16x16x32_bf16 v[8:11], v[186:189], v[212:215], v[8:11]
	v_mfma_f32_16x16x32_bf16 v[4:7], v[172:175], v[220:223], v[4:7]
	v_mfma_f32_16x16x32_bf16 v[0:3], v[186:189], v[220:223], v[0:3]
	s_barrier
	s_add_i32 s98, 0, 0x18000
	s_add_i32 s99, 0, 0x1c000
	v_add_u32_e32 v164, s98, v180
	v_add_u32_e32 v176, s99, v180
	ds_read_b128 v[128:131], v164
	ds_read_b128 v[132:135], v164 offset:1024
	ds_read_b128 v[136:139], v164 offset:2048
	ds_read_b128 v[164:167], v164 offset:3072
	ds_read_b128 v[168:171], v176
	ds_read_b128 v[172:175], v176 offset:1024
	ds_read_b128 v[182:185], v176 offset:2048
	ds_read_b128 v[186:189], v176 offset:3072
	s_add_u32 s38, s38, s88
	s_addc_u32 s39, s39, 0
	s_mov_b32 m0, s11
	v_lshl_add_u64 v[234:235], s[38:39], 0, v[140:141]
	ds_read_b128 v[190:193], v181 offset:32768
	ds_read_b128 v[194:197], v181 offset:33792
	ds_read_b128 v[198:201], v181 offset:34816
	ds_read_b128 v[202:205], v181 offset:35840
	ds_read_b128 v[206:209], v181 offset:36864
	ds_read_b128 v[212:215], v181 offset:37888
	ds_read_b128 v[216:219], v181 offset:38912
	ds_read_b128 v[220:223], v181 offset:39936
	global_load_lds_dwordx4 v[234:235], off
	v_lshl_add_u64 v[234:235], s[38:39], 0, v[144:145]
	s_mov_b32 m0, s55
	s_nop 0
	global_load_lds_dwordx4 v[234:235], off
	s_waitcnt vmcnt(8)
	s_waitcnt lgkmcnt(0)
	s_barrier
	v_mfma_f32_16x16x32_bf16 v[124:127], v[128:131], v[190:193], v[124:127]
	v_mfma_f32_16x16x32_bf16 v[120:123], v[136:139], v[190:193], v[120:123]
	v_mfma_f32_16x16x32_bf16 v[116:119], v[128:131], v[198:201], v[116:119]
	v_mfma_f32_16x16x32_bf16 v[112:115], v[136:139], v[198:201], v[112:115]
	v_mfma_f32_16x16x32_bf16 v[100:103], v[128:131], v[206:209], v[100:103]
	v_mfma_f32_16x16x32_bf16 v[96:99], v[136:139], v[206:209], v[96:99]
	v_mfma_f32_16x16x32_bf16 v[84:87], v[128:131], v[216:219], v[84:87]
	v_mfma_f32_16x16x32_bf16 v[80:83], v[136:139], v[216:219], v[80:83]
	v_mfma_f32_16x16x32_bf16 v[124:127], v[132:135], v[194:197], v[124:127]
	v_mfma_f32_16x16x32_bf16 v[120:123], v[164:167], v[194:197], v[120:123]
	v_mfma_f32_16x16x32_bf16 v[116:119], v[132:135], v[202:205], v[116:119]
	v_mfma_f32_16x16x32_bf16 v[112:115], v[164:167], v[202:205], v[112:115]
	v_mfma_f32_16x16x32_bf16 v[100:103], v[132:135], v[212:215], v[100:103]
	v_mfma_f32_16x16x32_bf16 v[96:99], v[164:167], v[212:215], v[96:99]
	v_mfma_f32_16x16x32_bf16 v[84:87], v[132:135], v[220:223], v[84:87]
	v_mfma_f32_16x16x32_bf16 v[80:83], v[164:167], v[220:223], v[80:83]
	v_mfma_f32_16x16x32_bf16 v[108:111], v[168:171], v[190:193], v[108:111]
	v_mfma_f32_16x16x32_bf16 v[104:107], v[182:185], v[190:193], v[104:107]
	v_mfma_f32_16x16x32_bf16 v[92:95], v[168:171], v[198:201], v[92:95]
	v_mfma_f32_16x16x32_bf16 v[88:91], v[182:185], v[198:201], v[88:91]
	v_mfma_f32_16x16x32_bf16 v[76:79], v[168:171], v[206:209], v[76:79]
	v_mfma_f32_16x16x32_bf16 v[72:75], v[182:185], v[206:209], v[72:75]
	v_mfma_f32_16x16x32_bf16 v[68:71], v[168:171], v[216:219], v[68:71]
	v_mfma_f32_16x16x32_bf16 v[64:67], v[182:185], v[216:219], v[64:67]
	v_mfma_f32_16x16x32_bf16 v[108:111], v[172:175], v[194:197], v[108:111]
	v_mfma_f32_16x16x32_bf16 v[104:107], v[186:189], v[194:197], v[104:107]
	v_mfma_f32_16x16x32_bf16 v[92:95], v[172:175], v[202:205], v[92:95]
	v_mfma_f32_16x16x32_bf16 v[88:91], v[186:189], v[202:205], v[88:91]
	v_mfma_f32_16x16x32_bf16 v[76:79], v[172:175], v[212:215], v[76:79]
	v_mfma_f32_16x16x32_bf16 v[72:75], v[186:189], v[212:215], v[72:75]
	v_mfma_f32_16x16x32_bf16 v[68:71], v[172:175], v[220:223], v[68:71]
	v_mfma_f32_16x16x32_bf16 v[64:67], v[186:189], v[220:223], v[64:67]
	s_barrier
; #define PG8_STAGE(bufoff, gbase, voff) do { _Pragma("unroll") for (int _i = 0; _i < 2; ++_i) \
;         __builtin_amdgcn_global_load_lds((const unsigned*)((const char*)(gbase) + (voff)[_i]), (PG8_LAS unsigned*)(lds + (bufoff) + ldsw + _i * 8192), 16, 0, 0); } while (0)
; #define PG8_LDA(dst, b, h) do { _Pragma("unroll") for (int m = 0; m < 4; ++m) _Pragma("unroll") for (int k = 0; k < 2; ++k) dst[m][k] = *(const PG8_LAS bf16x8*)(lds + PG8_SA(b, h) + aoff + m * 2048 + k * 1024); } while (0)
; #define PG8_MMA(ai, bj, At, Bt) do { __builtin_amdgcn_s_setprio(1); _Pragma("unroll") for (int m = 0; m < 4; ++m) _Pragma("unroll") for (int n = 0; n < 2; ++n) _Pragma("unroll") for (int k = 0; k < 2; ++k) \
;         acc[ai][bj][m][n] = __builtin_amdgcn_mfma_f32_16x16x32_bf16(Bt[n][k], At[m][k], acc[ai][bj][m][n], 0, 0, 0); __builtin_amdgcn_s_setprio(0); } while (0)
; #define PG8_WAIT_V(n) asm volatile("s_waitcnt vmcnt(" #n ")" ::: "memory")
; #define PG8_WAIT_L(n) asm volatile("s_waitcnt lgkmcnt(" #n ")" ::: "memory")
; #define PG8_BAR __builtin_amdgcn_s_barrier()
; #define PG8_SCHED __builtin_amdgcn_sched_barrier(0)
; template <class Epi, class Sched, bool ALIGN_EPI = false, bool SP2 = false>
; __device__ __forceinline__ void gemm_phase(PG8_LAS unsigned char* lds, const Gemm g, const Sched& S, const Epi& E, const int wid_) {
;     ...
;             PG8_LDA(At, 1, 1); PG8_STAGE(PG8_SB(1, 0), b3, voffB); PG8_STAGE(PG8_SB(1, 1), b3 + hstepB, voffB); PG8_STAGE(PG8_SA(1, 0), a3, voffA);
;             PG8_WAIT_V(8); PG8_WAIT_L(0); PG8_BAR; PG8_MMA(1, 0, At, B0); PG8_MMA(1, 1, At, B1); PG8_BAR; PG8_SCHED;
;     ...
;         if constexpr (ALIGN_EPI) { if (wr == 0) PG8_BAR; }
;         if constexpr (!Epi::AFTER_DRAIN) { E(acc, cur, wr, wc, fr, fq); S.done(cur); }
	s_add_i32 s38, s98, s83
	v_lshl_add_u64 v[178:179], v[178:179], 0, s[66:67]
	s_mov_b32 m0, s38
	ds_read_b128 v[190:193], v181 offset:49152
	ds_read_b128 v[194:197], v181 offset:50176
	ds_read_b128 v[198:201], v181 offset:51200
	ds_read_b128 v[202:205], v181 offset:52224
	ds_read_b128 v[206:209], v181 offset:53248
	ds_read_b128 v[212:215], v181 offset:54272
	ds_read_b128 v[216:219], v181 offset:55296
	ds_read_b128 v[220:223], v181 offset:56320
	global_load_lds_dwordx4 v[178:179], off
	v_lshl_add_u64 v[178:179], v[224:225], 0, s[66:67]
	s_add_i32 m0, s38, 0x2000
	s_add_i32 s38, s99, s83
	global_load_lds_dwordx4 v[178:179], off
	v_lshl_add_u64 v[178:179], v[226:227], 0, s[66:67]
	s_mov_b32 m0, s38
	s_nop 0
	global_load_lds_dwordx4 v[178:179], off
	v_lshl_add_u64 v[178:179], v[228:229], 0, s[66:67]
	s_add_i32 m0, s38, 0x2000
	s_nop 0
	global_load_lds_dwordx4 v[178:179], off
	v_lshl_add_u64 v[178:179], v[230:231], 0, s[66:67]
	s_mov_b32 m0, s33
	s_nop 0
	global_load_lds_dwordx4 v[178:179], off
	v_lshl_add_u64 v[178:179], v[232:233], 0, s[66:67]
	s_mov_b32 m0, s52
	s_nop 0
	global_load_lds_dwordx4 v[178:179], off
	s_waitcnt vmcnt(8)
	s_waitcnt lgkmcnt(0)
	s_barrier
	v_mfma_f32_16x16x32_bf16 v[60:63], v[128:131], v[190:193], v[60:63]
	v_mfma_f32_16x16x32_bf16 v[56:59], v[136:139], v[190:193], v[56:59]
	v_mfma_f32_16x16x32_bf16 v[52:55], v[128:131], v[198:201], v[52:55]
	v_mfma_f32_16x16x32_bf16 v[48:51], v[136:139], v[198:201], v[48:51]
	v_mfma_f32_16x16x32_bf16 v[36:39], v[128:131], v[206:209], v[36:39]
	v_mfma_f32_16x16x32_bf16 v[32:35], v[136:139], v[206:209], v[32:35]
	v_mfma_f32_16x16x32_bf16 v[20:23], v[128:131], v[216:219], v[20:23]
	v_mfma_f32_16x16x32_bf16 v[16:19], v[136:139], v[216:219], v[16:19]
	v_mfma_f32_16x16x32_bf16 v[60:63], v[132:135], v[194:197], v[60:63]
	v_mfma_f32_16x16x32_bf16 v[56:59], v[164:167], v[194:197], v[56:59]
	v_mfma_f32_16x16x32_bf16 v[52:55], v[132:135], v[202:205], v[52:55]
	v_mfma_f32_16x16x32_bf16 v[48:51], v[164:167], v[202:205], v[48:51]
	v_mfma_f32_16x16x32_bf16 v[36:39], v[132:135], v[212:215], v[36:39]
	v_mfma_f32_16x16x32_bf16 v[32:35], v[164:167], v[212:215], v[32:35]
	v_mfma_f32_16x16x32_bf16 v[20:23], v[132:135], v[220:223], v[20:23]
	v_mfma_f32_16x16x32_bf16 v[16:19], v[164:167], v[220:223], v[16:19]
	v_mfma_f32_16x16x32_bf16 v[44:47], v[168:171], v[190:193], v[44:47]
	v_mfma_f32_16x16x32_bf16 v[40:43], v[182:185], v[190:193], v[40:43]
	v_mfma_f32_16x16x32_bf16 v[28:31], v[168:171], v[198:201], v[28:31]
	v_mfma_f32_16x16x32_bf16 v[24:27], v[182:185], v[198:201], v[24:27]
	v_mfma_f32_16x16x32_bf16 v[12:15], v[168:171], v[206:209], v[12:15]
	v_mfma_f32_16x16x32_bf16 v[8:11], v[182:185], v[206:209], v[8:11]
	v_mfma_f32_16x16x32_bf16 v[4:7], v[168:171], v[216:219], v[4:7]
	v_mfma_f32_16x16x32_bf16 v[0:3], v[182:185], v[216:219], v[0:3]
	v_mfma_f32_16x16x32_bf16 v[44:47], v[172:175], v[194:197], v[44:47]
	v_mfma_f32_16x16x32_bf16 v[40:43], v[186:189], v[194:197], v[40:43]
	v_mfma_f32_16x16x32_bf16 v[28:31], v[172:175], v[202:205], v[28:31]
	v_mfma_f32_16x16x32_bf16 v[24:27], v[186:189], v[202:205], v[24:27]
	v_mfma_f32_16x16x32_bf16 v[12:15], v[172:175], v[212:215], v[12:15]
	v_mfma_f32_16x16x32_bf16 v[8:11], v[186:189], v[212:215], v[8:11]
	v_mfma_f32_16x16x32_bf16 v[4:7], v[172:175], v[220:223], v[4:7]
	v_mfma_f32_16x16x32_bf16 v[0:3], v[186:189], v[220:223], v[0:3]
	s_barrier
	s_add_u32 s49, s49, 0x100
	s_addc_u32 s62, s62, 0
	s_add_u32 s6, s6, 0x100
	s_addc_u32 s7, s7, 0
	s_cmp_ge_u32 s97, s71
	s_mov_b32 s38, s97
	s_cbranch_scc0 .LBB0_380
	s_setprio 0
	s_and_b64 vcc, exec, s[94:95]
	s_cbranch_vccz .LBB0_384
	s_barrier
	v_lshl_add_u32 v164, s48, 8, v153
	s_cmp_lt_i32 s37, 2
	s_mov_b64 s[6:7], -1
	s_cbranch_scc0 .LBB0_385
